# v22 + small_gemm K loops issue 16/24 fragment loads per group before the MFMAs; GEMM phase prologue drain removed; tile epilogues of the two wave halves no longer barrier-aligned
# baseline (speedup 1.0000x reference)
; #define PG8_BAR __builtin_amdgcn_s_barrier()
; template <class Epi, class Sched, bool ALIGN_EPI = false, bool SP2 = false>
; __device__ __forceinline__ void gemm_phase(PG8_LAS unsigned char* lds, const Gemm g, const Sched& S, const Epi& E) {
;     ...
;         if constexpr (ALIGN_EPI) { if (wr == 0) PG8_BAR; }
;         if constexpr (!Epi::AFTER_DRAIN) { E(acc, cur, wr, wc, fr, fq); S.done(cur); }
.Lk_loop_done:
.LBB0_691:
	s_lshl_b32 s30, s40, 8
	s_cmp_gt_i32 s24, 6
	s_mov_b64 s[16:17], -1
	s_cbranch_scc0 .LBB0_695
	s_cmp_lt_i32 s40, 4
	s_mov_b64 s[8:9], s[88:89]
	s_mov_b32 s27, s37
	s_mov_b32 s31, s30
	s_cbranch_scc1 .LBB0_694
	s_add_i32 s31, s30, 0xfffffc00
	s_movk_i32 s27, 0x200
	s_mov_b64 s[8:9], 0x10a00000

; #define PG8_BAR __builtin_amdgcn_s_barrier()
; template <class Epi, class Sched, bool ALIGN_EPI = false, bool SP2 = false>
; __device__ __forceinline__ void gemm_phase(PG8_LAS unsigned char* lds, const Gemm g, const Sched& S, const Epi& E) {
;     ...
;         cur = nxt; cA = nA; cB = nB; ++ui;
;         if constexpr (ALIGN_EPI) { if (wr == 1) PG8_BAR; }
.LBB0_975:
	v_readlane_b32 s8, v251, 61
	v_readlane_b32 s9, v251, 62
	s_branch .LBB0_675

; #define PG8_WAIT_V(n) asm volatile("s_waitcnt vmcnt(" #n ")" ::: "memory")
; #define PG8_BAR __builtin_amdgcn_s_barrier()
; template <class Epi, class Sched, bool ALIGN_EPI = false, bool SP2 = false>
; __device__ __forceinline__ void gemm_phase(PG8_LAS unsigned char* lds, const Gemm g, const Sched& S, const Epi& E) {
;     ...
;     PG8_WAIT_V(0);
;     if constexpr (!ALIGN_EPI) { if (wr == 0) PG8_BAR; }
;     PG8_BAR;
.LBB0_1058:
	s_waitcnt vmcnt(0)
	v_readlane_b32 s26, v251, 55
	v_readlane_b32 s76, v251, 51
	v_readlane_b32 s87, v251, 54
	v_readlane_b32 s27, v251, 56
	s_and_b64 vcc, exec, s[94:95]
	s_cbranch_vccz .Lgemm_tail_bar
	s_barrier
.Lgemm_tail_bar:
	s_barrier
	s_andn2_b64 vcc, exec, s[56:57]
	s_cbranch_vccnz .LBB0_1135
